# speedup vs baseline: 1.0285x; 1.0003x over previous
.LBB0_1727:
	s_waitcnt vmcnt(1)
	v_mov_b32_e32 v52, v244
	v_mov_b32_e32 v0, 0
	s_andn2_b64 vcc, exec, s[2:3]
	v_lshlrev_b32_e32 v53, 4, v52
	v_ashrrev_i32_e32 v110, 4, v52
	v_mov_b32_e32 v1, 0
	v_mov_b32_e32 v2, 0
	v_mov_b32_e32 v3, 0
	v_mov_b32_e32 v4, 0
	v_mov_b32_e32 v5, 0
	v_mov_b32_e32 v6, 0
	v_mov_b32_e32 v7, 0
	v_mov_b32_e32 v8, 0
	v_mov_b32_e32 v9, 0
	v_mov_b32_e32 v10, 0
	v_mov_b32_e32 v11, 0
	v_mov_b32_e32 v12, 0
	v_mov_b32_e32 v13, 0
	v_mov_b32_e32 v14, 0
	v_mov_b32_e32 v15, 0
	v_mov_b32_e32 v16, 0
	v_mov_b32_e32 v17, 0
	v_mov_b32_e32 v18, 0
	v_mov_b32_e32 v19, 0
	v_mov_b32_e32 v20, 0
	v_mov_b32_e32 v21, 0
	v_mov_b32_e32 v22, 0
	v_mov_b32_e32 v23, 0
	v_mov_b32_e32 v24, 0
	v_mov_b32_e32 v25, 0
	v_mov_b32_e32 v26, 0
	v_mov_b32_e32 v27, 0
	v_mov_b32_e32 v28, 0
	v_mov_b32_e32 v29, 0
	v_mov_b32_e32 v30, 0
	v_mov_b32_e32 v31, 0
	v_mov_b32_e32 v32, 0
	v_mov_b32_e32 v33, 0
	v_mov_b32_e32 v34, 0
	v_mov_b32_e32 v35, 0
	v_mov_b32_e32 v36, 0
	v_mov_b32_e32 v37, 0
	v_mov_b32_e32 v38, 0
	v_mov_b32_e32 v39, 0
	v_mov_b32_e32 v40, 0
	v_mov_b32_e32 v41, 0
	v_mov_b32_e32 v42, 0
	v_mov_b32_e32 v43, 0
	v_mov_b32_e32 v44, 0
	v_mov_b32_e32 v45, 0
	v_mov_b32_e32 v46, 0
	v_mov_b32_e32 v47, 0
	s_waitcnt vmcnt(0)
	v_mov_b32_e32 v48, 0
	v_mov_b32_e32 v49, 0
	v_mov_b32_e32 v50, 0
	v_mov_b32_e32 v51, 0
	s_cbranch_vccnz .LBB0_1729
	s_add_i32 s98, s36, 0xfffffee8
	s_cmpk_lt_i32 s36, 0x8f8
	s_cselect_b32 s98, s36, s98
	s_add_i32 s99, s36, 0xffffff78
	s_cmpk_lt_i32 s36, 0x910
	s_cselect_b32 s98, s98, s99
	s_add_i32 s99, s36, 0xfffffc18
	s_cmpk_lt_i32 s36, 0xce0
	s_cselect_b32 s98, s98, s99
	s_cmp_eq_u32 s52, s77
	s_cselect_b32 s98, s36, s98
	s_add_i32 s0, s98, 0xffffff40
	s_ashr_i32 s0, s0, 5
	s_mul_hi_i32 s2, s0, 0x55555556
	s_lshr_b32 s3, s2, 31
	s_add_i32 s3, s2, s3
	s_mul_i32 s2, s3, 3
	s_sub_i32 s0, s0, s2
	s_lshl_b32 s6, s0, 1
	s_lshr_b32 s2, 32, s6
	s_and_b32 s1, s98, 31
	s_sub_i32 s5, 5, s6
	s_add_i32 s2, s2, -1
	s_lshr_b32 s5, s1, s5
	s_and_b32 s1, s2, s1
	s_lshl_b32 s2, s1, 6
	s_lshl_b32 s0, s0, 5
	s_and_b32 s1, s3, -8
	s_and_b32 s4, s3, 7
	s_add_i32 s0, s0, s1
	s_or_b32 s0, s0, s4
	s_lshl_b32 s3, s3, 8
	s_ashr_i32 s1, s0, 31
	s_and_b32 s3, s3, 0xfffff800
	s_lshr_b32 s7, 0x800, s6
	s_lshl_b64 s[0:1], s[0:1], 19
	s_addk_i32 s2, 0xff80
	s_or_b32 s3, s5, s3
	s_lshl_b32 s4, s4, 8
	v_readlane_b32 s10, v249, 10
	v_readlane_b32 s11, v249, 11
	s_add_u32 s4, s10, s4
	s_mul_i32 s8, s5, s7
	s_addc_u32 s5, s11, 0
	v_and_b32_e32 v0, 0xf0, v53
	v_mov_b32_e32 v1, 0
	v_lshl_add_u64 v[16:17], s[4:5], 0, v[0:1]
	v_add_u32_e32 v0, s2, v110
	v_max_i32_e32 v0, 0, v0
	v_lshlrev_b32_e32 v0, s6, v0
	v_add_u32_e32 v0, s3, v0
	v_ashrrev_i32_e32 v1, 31, v0
	v_lshlrev_b64 v[0:1], 11, v[0:1]
	v_add_u32_e32 v28, 0x200, v52
	v_lshl_add_u64 v[8:9], v[16:17], 0, v[0:1]
	v_ashrrev_i32_e32 v0, 4, v28
	v_add_u32_e32 v0, s2, v0
	v_max_i32_e32 v0, 0, v0
	v_lshlrev_b32_e32 v0, s6, v0
	v_add_u32_e32 v0, s3, v0
	v_ashrrev_i32_e32 v1, 31, v0
	v_lshlrev_b64 v[0:1], 11, v[0:1]
	v_add_u32_e32 v36, 0x400, v52
	v_lshl_add_u64 v[10:11], v[16:17], 0, v[0:1]
	global_load_dwordx4 v[0:3], v[8:9], off
	global_load_dwordx4 v[4:7], v[10:11], off
	v_ashrrev_i32_e32 v8, 4, v36
	v_add_u32_e32 v8, s2, v8
	v_max_i32_e32 v8, 0, v8
	v_lshlrev_b32_e32 v8, s6, v8
	v_add_u32_e32 v8, s3, v8
	v_ashrrev_i32_e32 v9, 31, v8
	v_lshlrev_b64 v[8:9], 11, v[8:9]
	v_add_u32_e32 v37, 0x600, v52
	v_lshl_add_u64 v[18:19], v[16:17], 0, v[8:9]
	v_ashrrev_i32_e32 v8, 4, v37
	v_add_u32_e32 v8, s2, v8
	v_max_i32_e32 v8, 0, v8
	v_lshlrev_b32_e32 v8, s6, v8
	v_add_u32_e32 v8, s3, v8
	v_ashrrev_i32_e32 v9, 31, v8
	v_lshlrev_b64 v[8:9], 11, v[8:9]
	v_add_u32_e32 v44, 0x800, v52
	v_lshl_add_u64 v[20:21], v[16:17], 0, v[8:9]
	global_load_dwordx4 v[8:11], v[18:19], off
	global_load_dwordx4 v[12:15], v[20:21], off
	v_ashrrev_i32_e32 v18, 4, v44
	v_add_u32_e32 v18, s2, v18
	v_max_i32_e32 v18, 0, v18
	v_lshlrev_b32_e32 v18, s6, v18
	v_add_u32_e32 v18, s3, v18
	v_ashrrev_i32_e32 v19, 31, v18
	v_lshlrev_b64 v[18:19], 11, v[18:19]
	v_add_u32_e32 v45, 0xa00, v52
	v_lshl_add_u64 v[24:25], v[16:17], 0, v[18:19]
	v_ashrrev_i32_e32 v18, 4, v45
	v_add_u32_e32 v18, s2, v18
	v_max_i32_e32 v18, 0, v18
	v_lshlrev_b32_e32 v18, s6, v18
	v_add_u32_e32 v18, s3, v18
	v_ashrrev_i32_e32 v19, 31, v18
	s_add_u32 s0, s85, s0
	v_lshlrev_b64 v[18:19], 11, v[18:19]
	s_addc_u32 s1, s86, s1
	s_lshl_b32 s3, s8, 1
	v_lshl_add_u64 v[26:27], v[16:17], 0, v[18:19]
	global_load_dwordx4 v[16:19], v[24:25], off
	global_load_dwordx4 v[20:23], v[26:27], off
	s_add_u32 s0, s0, s3
	v_min_i32_e32 v25, 0xcff, v52
	s_mov_b32 s3, 0x4ec4ec4f
	v_mul_hi_i32 v24, v25, s3
	v_lshrrev_b32_e32 v26, 31, v24
	v_ashrrev_i32_e32 v24, 3, v24
	v_add_u32_e32 v24, v24, v26
	v_mul_lo_u32 v26, v24, 26
	v_sub_u32_e32 v25, v25, v26
	v_lshl_add_u32 v25, v25, 3, s2
	s_addc_u32 s1, s1, 0
	s_add_i32 s7, s7, -8
	v_max_i32_e32 v25, 0, v25
	v_min_i32_e32 v26, s7, v25
	v_ashrrev_i32_e32 v25, 31, v24
	v_lshlrev_b64 v[24:25], 12, v[24:25]
	v_lshl_add_u64 v[24:25], s[0:1], 0, v[24:25]
	v_ashrrev_i32_e32 v27, 31, v26
	v_lshl_add_u64 v[32:33], v[26:27], 1, v[24:25]
	v_min_i32_e32 v25, 0xcff, v28
	v_mul_hi_i32 v24, v25, s3
	v_lshrrev_b32_e32 v26, 31, v24
	v_ashrrev_i32_e32 v24, 3, v24
	v_add_u32_e32 v24, v24, v26
	v_mul_lo_u32 v26, v24, 26
	v_sub_u32_e32 v25, v25, v26
	v_lshl_add_u32 v25, v25, 3, s2
	v_max_i32_e32 v25, 0, v25
	v_min_i32_e32 v26, s7, v25
	v_ashrrev_i32_e32 v25, 31, v24
	v_lshlrev_b64 v[24:25], 12, v[24:25]
	v_lshl_add_u64 v[24:25], s[0:1], 0, v[24:25]
	v_ashrrev_i32_e32 v27, 31, v26
	v_lshl_add_u64 v[34:35], v[26:27], 1, v[24:25]
	global_load_dwordx4 v[24:27], v[32:33], off
	global_load_dwordx4 v[28:31], v[34:35], off
	v_min_i32_e32 v33, 0xcff, v36
	v_mul_hi_i32 v32, v33, s3
	v_lshrrev_b32_e32 v34, 31, v32
	v_ashrrev_i32_e32 v32, 3, v32
	v_add_u32_e32 v32, v32, v34
	v_mul_lo_u32 v34, v32, 26
	v_sub_u32_e32 v33, v33, v34
	v_lshl_add_u32 v33, v33, 3, s2
	v_max_i32_e32 v33, 0, v33
	v_min_i32_e32 v34, s7, v33
	v_ashrrev_i32_e32 v33, 31, v32
	v_lshlrev_b64 v[32:33], 12, v[32:33]
	v_lshl_add_u64 v[32:33], s[0:1], 0, v[32:33]
	v_ashrrev_i32_e32 v35, 31, v34
	v_lshl_add_u64 v[40:41], v[34:35], 1, v[32:33]
	v_min_i32_e32 v33, 0xcff, v37
	v_mul_hi_i32 v32, v33, s3
	v_lshrrev_b32_e32 v34, 31, v32
	v_ashrrev_i32_e32 v32, 3, v32
	v_add_u32_e32 v32, v32, v34
	v_mul_lo_u32 v34, v32, 26
	v_sub_u32_e32 v33, v33, v34
	v_lshl_add_u32 v33, v33, 3, s2
	v_max_i32_e32 v33, 0, v33
	v_min_i32_e32 v34, s7, v33
	v_ashrrev_i32_e32 v33, 31, v32
	v_lshlrev_b64 v[32:33], 12, v[32:33]
	v_lshl_add_u64 v[32:33], s[0:1], 0, v[32:33]
	v_ashrrev_i32_e32 v35, 31, v34
	v_lshl_add_u64 v[42:43], v[34:35], 1, v[32:33]
	global_load_dwordx4 v[32:35], v[40:41], off
	global_load_dwordx4 v[36:39], v[42:43], off
	v_min_i32_e32 v41, 0xcff, v44
	v_mul_hi_i32 v40, v41, s3
	v_lshrrev_b32_e32 v42, 31, v40
	v_ashrrev_i32_e32 v40, 3, v40
	v_add_u32_e32 v40, v40, v42
	v_mul_lo_u32 v42, v40, 26
	v_sub_u32_e32 v41, v41, v42
	v_lshl_add_u32 v41, v41, 3, s2
	v_max_i32_e32 v41, 0, v41
	v_min_i32_e32 v42, s7, v41
	v_ashrrev_i32_e32 v41, 31, v40
	v_lshlrev_b64 v[40:41], 12, v[40:41]
	v_lshl_add_u64 v[40:41], s[0:1], 0, v[40:41]
	v_ashrrev_i32_e32 v43, 31, v42
	v_lshl_add_u64 v[48:49], v[42:43], 1, v[40:41]
	v_min_i32_e32 v41, 0xcff, v45
	v_mul_hi_i32 v40, v41, s3
	v_lshrrev_b32_e32 v42, 31, v40
	v_ashrrev_i32_e32 v40, 3, v40
	v_add_u32_e32 v40, v40, v42
	v_mul_lo_u32 v42, v40, 26
	v_sub_u32_e32 v41, v41, v42
	v_lshl_add_u32 v41, v41, 3, s2
	v_max_i32_e32 v41, 0, v41
	v_min_i32_e32 v42, s7, v41
	v_ashrrev_i32_e32 v41, 31, v40
	v_lshlrev_b64 v[40:41], 12, v[40:41]
	v_lshl_add_u64 v[40:41], s[0:1], 0, v[40:41]
	v_ashrrev_i32_e32 v43, 31, v42
	v_lshl_add_u64 v[50:51], v[42:43], 1, v[40:41]
	global_load_dwordx4 v[40:43], v[48:49], off
	global_load_dwordx4 v[44:47], v[50:51], off
	v_min_i32_e32 v48, 0xff, v52
	v_add_u32_e32 v49, 0xc00, v48
	v_mul_hi_i32 v48, v49, s3
	v_lshrrev_b32_e32 v50, 31, v48
	v_ashrrev_i32_e32 v48, 3, v48
	v_add_u32_e32 v48, v48, v50
	v_mul_lo_u32 v50, v48, 26
	v_sub_u32_e32 v49, v49, v50
	v_lshl_add_u32 v49, v49, 3, s2
	v_max_i32_e32 v49, 0, v49
	v_min_i32_e32 v50, s7, v49
	v_ashrrev_i32_e32 v49, 31, v48
	v_lshlrev_b64 v[48:49], 12, v[48:49]
	v_lshl_add_u64 v[48:49], s[0:1], 0, v[48:49]
	v_ashrrev_i32_e32 v51, 31, v50
	v_lshl_add_u64 v[48:49], v[50:51], 1, v[48:49]
	global_load_dwordx4 v[48:51], v[48:49], off

.LBB0_1732:
	s_waitcnt vmcnt(40)
	v_lshrrev_b32_e32 v52, 16, v27
	v_lshrrev_b32_e32 v53, 16, v26
	v_lshrrev_b32_e32 v54, 16, v25
	v_lshrrev_b32_e32 v55, 16, v24
	s_barrier
	ds_write_b128 v123, v[0:3]
	ds_write_b128 v124, v[4:7]
	ds_write_b128 v125, v[8:11]
	ds_write_b128 v126, v[12:15]
	ds_write_b128 v127, v[16:19]
	ds_write_b128 v128, v[20:23]
	s_and_saveexec_b64 s[16:17], s[2:3]
	v_perm_b32 v56, v55, v24, s60
	v_perm_b32 v57, v54, v25, s60
	v_perm_b32 v58, v53, v26, s60
	v_perm_b32 v59, v52, v27, s60
	ds_write_b128 v129, v[56:59] offset:52224
	s_or_b64 exec, exec, s[16:17]
	v_lshrrev_b32_e32 v56, 16, v31
	v_lshrrev_b32_e32 v57, 16, v30
	v_lshrrev_b32_e32 v58, 16, v29
	v_lshrrev_b32_e32 v59, 16, v28
	s_and_saveexec_b64 s[16:17], s[4:5]
	v_perm_b32 v60, v59, v28, s60
	v_perm_b32 v61, v58, v29, s60
	v_perm_b32 v62, v57, v30, s60
	v_perm_b32 v63, v56, v31, s60
	ds_write_b128 v130, v[60:63] offset:52224
	s_or_b64 exec, exec, s[16:17]
	v_lshrrev_b32_e32 v60, 16, v35
	v_lshrrev_b32_e32 v61, 16, v34
	v_lshrrev_b32_e32 v62, 16, v33
	v_lshrrev_b32_e32 v63, 16, v32
	s_and_saveexec_b64 s[16:17], s[6:7]
	v_perm_b32 v64, v63, v32, s60
	v_perm_b32 v65, v62, v33, s60
	v_perm_b32 v66, v61, v34, s60
	v_perm_b32 v67, v60, v35, s60
	ds_write_b128 v131, v[64:67] offset:52224
	s_or_b64 exec, exec, s[16:17]
	v_lshrrev_b32_e32 v64, 16, v39
	v_lshrrev_b32_e32 v65, 16, v38
	v_lshrrev_b32_e32 v66, 16, v37
	v_lshrrev_b32_e32 v67, 16, v36
	s_and_saveexec_b64 s[16:17], s[8:9]
	v_perm_b32 v68, v67, v36, s60
	v_perm_b32 v69, v66, v37, s60
	v_perm_b32 v70, v65, v38, s60
	v_perm_b32 v71, v64, v39, s60
	ds_write_b128 v132, v[68:71] offset:52224
	s_or_b64 exec, exec, s[16:17]
	v_lshrrev_b32_e32 v68, 16, v43
	v_lshrrev_b32_e32 v69, 16, v42
	v_lshrrev_b32_e32 v70, 16, v41
	v_lshrrev_b32_e32 v71, 16, v40
	s_and_saveexec_b64 s[16:17], s[10:11]
	v_perm_b32 v72, v71, v40, s60
	v_perm_b32 v73, v70, v41, s60
	v_perm_b32 v74, v69, v42, s60
	v_perm_b32 v75, v68, v43, s60
	ds_write_b128 v133, v[72:75] offset:52224
	s_or_b64 exec, exec, s[16:17]
	v_lshrrev_b32_e32 v72, 16, v47
	v_lshrrev_b32_e32 v73, 16, v46
	v_lshrrev_b32_e32 v74, 16, v45
	v_lshrrev_b32_e32 v75, 16, v44
	s_and_saveexec_b64 s[16:17], s[12:13]
	v_perm_b32 v76, v75, v44, s60
	v_perm_b32 v77, v74, v45, s60
	v_perm_b32 v78, v73, v46, s60
	v_perm_b32 v79, v72, v47, s60
	ds_write_b128 v134, v[76:79] offset:52224
	s_or_b64 exec, exec, s[16:17]
	v_lshrrev_b32_e32 v76, 16, v51
	v_lshrrev_b32_e32 v77, 16, v50
	v_lshrrev_b32_e32 v78, 16, v49
	v_lshrrev_b32_e32 v79, 16, v48
	s_and_saveexec_b64 s[16:17], s[14:15]
	v_perm_b32 v80, v79, v48, s60
	v_perm_b32 v81, v78, v49, s60
	v_perm_b32 v82, v77, v50, s60
	v_perm_b32 v83, v76, v51, s60
	ds_write_b128 v135, v[80:83] offset:52224
	s_or_b64 exec, exec, s[16:17]
	s_add_i32 s74, s36, s52
	s_cmp_ge_i32 s74, s33
	s_cselect_b64 s[48:49], -1, 0
	s_and_b64 vcc, exec, s[48:49]
	s_waitcnt lgkmcnt(0)
	s_barrier
	s_cbranch_vccnz .LBB0_1748
	s_add_i32 s98, s74, 0xfffffee8
	s_cmpk_lt_i32 s74, 0x8f8
	s_cselect_b32 s98, s74, s98
	s_add_i32 s99, s74, 0xffffff78
	s_cmpk_lt_i32 s74, 0x910
	s_cselect_b32 s98, s98, s99
	s_add_i32 s99, s74, 0xfffffc18
	s_cmpk_lt_i32 s74, 0xce0
	s_cselect_b32 s98, s98, s99
	s_cmp_eq_u32 s52, s77
	s_cselect_b32 s98, s74, s98
	s_add_i32 s0, s98, 0xffffff40
	s_ashr_i32 s0, s0, 5
	s_mul_hi_i32 s17, s0, 0x55555556
	s_lshr_b32 s18, s17, 31
	s_add_i32 s18, s17, s18
	s_mul_i32 s17, s18, 3
	s_sub_i32 s0, s0, s17
	s_lshl_b32 s20, s0, 1
	s_lshr_b32 s17, 32, s20
	s_and_b32 s16, s98, 31
	s_sub_i32 s22, 5, s20
	s_add_i32 s17, s17, -1
	s_lshr_b32 s22, s16, s22
	s_and_b32 s16, s17, s16
	s_lshl_b32 s23, s16, 6
	s_lshl_b32 s0, s0, 5
	s_and_b32 s16, s18, -8
	s_and_b32 s19, s18, 7
	s_add_i32 s0, s0, s16
	s_or_b32 s16, s0, s19
	s_lshl_b32 s0, s18, 8
	s_ashr_i32 s17, s16, 31
	s_and_b32 s0, s0, 0xfffff800
	s_lshr_b32 s21, 0x800, s20
	s_lshl_b64 s[16:17], s[16:17], 19
	s_addk_i32 s23, 0xff80
	s_or_b32 s18, s22, s0
	s_lshl_b32 s0, s19, 8
	s_mul_i32 s24, s22, s21
	v_lshl_add_u64 v[16:17], v[86:87], 0, s[0:1]
	s_add_u32 s0, s85, s16
	s_addc_u32 s17, s86, s17
	s_lshl_b32 s16, s24, 1
	s_add_u32 s16, s0, s16
	v_add_u32_e32 v24, s23, v116
	v_add_u32_e32 v32, s23, v118
	v_add_u32_e32 v40, s23, v120
	s_addc_u32 s17, s17, 0
	s_add_i32 s21, s21, -8
	v_max_i32_e32 v24, 0, v24
	v_max_i32_e32 v32, 0, v32
	v_max_i32_e32 v40, 0, v40
	v_add_u32_e32 v0, s23, v110
	v_add_u32_e32 v2, s23, v111
	v_add_u32_e32 v8, s23, v112
	v_add_u32_e32 v10, s23, v113
	v_add_u32_e32 v18, s23, v114
	v_add_u32_e32 v20, s23, v115
	v_min_i32_e32 v24, s21, v24
	v_min_i32_e32 v32, s21, v32
	v_min_i32_e32 v40, s21, v40
	v_max_i32_e32 v0, 0, v0
	v_max_i32_e32 v2, 0, v2
	v_max_i32_e32 v8, 0, v8
	v_max_i32_e32 v10, 0, v10
	v_max_i32_e32 v18, 0, v18
	v_max_i32_e32 v20, 0, v20
	v_lshl_add_u64 v[26:27], s[16:17], 0, v[88:89]
	v_ashrrev_i32_e32 v25, 31, v24
	v_lshl_add_u64 v[34:35], s[16:17], 0, v[92:93]
	v_ashrrev_i32_e32 v33, 31, v32
	v_lshl_add_u64 v[42:43], s[16:17], 0, v[96:97]
	v_ashrrev_i32_e32 v41, 31, v40
	v_lshlrev_b32_e32 v0, s20, v0
	v_lshlrev_b32_e32 v2, s20, v2
	v_lshlrev_b32_e32 v8, s20, v8
	v_lshlrev_b32_e32 v10, s20, v10
	v_lshlrev_b32_e32 v18, s20, v18
	v_lshlrev_b32_e32 v20, s20, v20
	v_lshl_add_u64 v[24:25], v[24:25], 1, v[26:27]
	v_add_u32_e32 v26, s23, v117
	v_lshl_add_u64 v[32:33], v[32:33], 1, v[34:35]
	v_add_u32_e32 v34, s23, v119
	v_lshl_add_u64 v[40:41], v[40:41], 1, v[42:43]
	v_add_u32_e32 v42, s23, v121
	v_add_u32_e32 v48, s23, v122
	v_add_u32_e32 v0, s18, v0
	v_add_u32_e32 v2, s18, v2
	v_add_u32_e32 v8, s18, v8
	v_add_u32_e32 v10, s18, v10
	v_add_u32_e32 v18, s18, v18
	v_add_u32_e32 v20, s18, v20
	v_max_i32_e32 v26, 0, v26
	v_max_i32_e32 v34, 0, v34
	v_max_i32_e32 v42, 0, v42
	v_max_i32_e32 v48, 0, v48
	v_ashrrev_i32_e32 v1, 31, v0
	v_ashrrev_i32_e32 v3, 31, v2
	v_ashrrev_i32_e32 v9, 31, v8
	v_ashrrev_i32_e32 v11, 31, v10
	v_ashrrev_i32_e32 v19, 31, v18
	v_ashrrev_i32_e32 v21, 31, v20
	v_min_i32_e32 v26, s21, v26
	v_min_i32_e32 v34, s21, v34
	v_min_i32_e32 v42, s21, v42
	v_min_i32_e32 v48, s21, v48
	v_lshlrev_b64 v[0:1], 11, v[0:1]
	v_lshlrev_b64 v[2:3], 11, v[2:3]
	v_lshlrev_b64 v[8:9], 11, v[8:9]
	v_lshlrev_b64 v[10:11], 11, v[10:11]
	v_lshlrev_b64 v[18:19], 11, v[18:19]
	v_lshlrev_b64 v[20:21], 11, v[20:21]
	v_lshl_add_u64 v[28:29], s[16:17], 0, v[90:91]
	v_ashrrev_i32_e32 v27, 31, v26
	v_lshl_add_u64 v[36:37], s[16:17], 0, v[94:95]
	v_ashrrev_i32_e32 v35, 31, v34
	v_lshl_add_u64 v[44:45], s[16:17], 0, v[98:99]
	v_ashrrev_i32_e32 v43, 31, v42
	v_lshl_add_u64 v[50:51], s[16:17], 0, v[100:101]
	v_ashrrev_i32_e32 v49, 31, v48
	v_lshl_add_u64 v[0:1], v[16:17], 0, v[0:1]
	v_lshl_add_u64 v[4:5], v[16:17], 0, v[2:3]
	v_lshl_add_u64 v[8:9], v[16:17], 0, v[8:9]
	v_lshl_add_u64 v[12:13], v[16:17], 0, v[10:11]
	v_lshl_add_u64 v[18:19], v[16:17], 0, v[18:19]
	v_lshl_add_u64 v[20:21], v[16:17], 0, v[20:21]
	v_lshl_add_u64 v[28:29], v[26:27], 1, v[28:29]
	v_lshl_add_u64 v[36:37], v[34:35], 1, v[36:37]
	v_lshl_add_u64 v[44:45], v[42:43], 1, v[44:45]
	v_lshl_add_u64 v[48:49], v[48:49], 1, v[50:51]
	s_branch .LBB0_1749

.LBB0_1749:
	s_add_i32 s98, s36, 0xfffffee8
	s_cmpk_lt_i32 s36, 0x8f8
	s_cselect_b32 s98, s36, s98
	s_add_i32 s99, s36, 0xffffff78
	s_cmpk_lt_i32 s36, 0x910
	s_cselect_b32 s98, s98, s99
	s_add_i32 s99, s36, 0xfffffc18
	s_cmpk_lt_i32 s36, 0xce0
	s_cselect_b32 s98, s98, s99
	s_cmp_eq_u32 s52, s77
	s_cselect_b32 s98, s36, s98
	s_add_i32 s0, s98, 0xffffff40
	s_ashr_i32 s0, s0, 5
	s_mul_hi_i32 s17, s0, 0x55555556
	s_lshr_b32 s18, s17, 31
	s_add_i32 s20, s17, s18
	s_mul_i32 s17, s20, 3
	s_sub_i32 s21, s0, s17
	s_lshl_b32 s0, s21, 1
	s_lshr_b32 s17, 32, s0
	v_mov_b32_e32 v52, v244
	s_and_b32 s16, s98, 31
	s_sub_i32 s18, 5, s0
	s_add_i32 s17, s17, -1
	s_lshr_b32 s22, s16, s18
	s_and_b32 s28, s17, s16
	s_lshl_b32 s16, s20, 2
	v_ashrrev_i32_e32 v53, 6, v52
	v_and_b32_e32 v138, 15, v52
	v_bfe_u32 v58, v52, 4, 2
	v_ashrrev_i32_e32 v52, 7, v52
	s_and_b32 s16, s16, 28
	s_lshl_b32 s75, s28, 6
	v_add_u32_e32 v52, s16, v52
	s_mul_i32 s16, s21, 0x4200000
	s_mul_hi_i32 s17, s21, 0x4200000
	s_add_u32 s16, s54, s16
	s_addc_u32 s17, s55, s17
	s_mul_i32 s18, s21, 0x108000
	s_mul_hi_i32 s19, s21, 0x108000
	s_add_u32 s18, s58, s18
	s_addc_u32 s19, s59, s19
	s_lshl_b32 s20, s20, 8
	s_and_b32 s20, s20, 0xfffff800
	s_or_b32 s76, s22, s20
	s_lshl_b32 s20, s21, 12
	v_mul_lo_u32 v54, v53, s61
	s_ashr_i32 s21, s20, 31
	v_add_u32_e32 v59, 0x1a400, v54
	v_lshlrev_b32_e32 v53, 5, v53
	s_lshl_b64 s[20:21], s[20:21], 1
	v_lshlrev_b32_e32 v54, 7, v52
	v_lshlrev_b32_e32 v141, 2, v58
	v_and_b32_e32 v139, 32, v53
	s_add_u32 s20, s80, s20
	v_ashrrev_i32_e32 v55, 31, v54
	v_sub_u32_e32 v60, v141, v138
	v_ashrrev_i32_e32 v53, 31, v52
	s_addc_u32 s21, s81, s21
	v_lshlrev_b64 v[54:55], 1, v[54:55]
	v_lshl_add_u64 v[106:107], v[52:53], 2, s[18:19]
	v_add_u32_e32 v52, 1, v60
	v_lshl_add_u64 v[56:57], s[20:21], 0, v[54:55]
	v_cmp_gt_u32_e64 s[20:21], s63, v52
	v_add_u32_e32 v52, 0x82, v60
	v_add_u32_e32 v61, 0x80, v60
	v_cmp_gt_u32_e64 s[34:35], s63, v52
	v_add_u32_e32 v52, 2, v60
	s_cmp_gt_u32 s28, 1
	v_cmp_gt_u32_e32 vcc, s63, v61
	v_cmp_gt_u32_e64 s[22:23], s63, v52
	v_add_u32_e32 v52, 0x83, v60
	s_cselect_b64 s[40:41], -1, 0
	v_lshlrev_b32_e32 v84, 4, v58
	v_cmp_gt_u32_e64 s[36:37], s63, v52
	v_add_u32_e32 v52, 3, v60
	s_and_b64 s[26:27], vcc, s[40:41]
	v_lshl_add_u64 v[102:103], v[56:57], 0, v[84:85]
	v_mad_u32_u24 v62, v138, s62, v59
	v_lshl_add_u64 v[54:55], s[16:17], 0, v[54:55]
	v_lshlrev_b32_e32 v56, 1, v138
	v_mov_b32_e32 v57, v85
	v_cmp_lt_u32_e64 s[30:31], s64, v60
	v_cmp_gt_u32_e64 s[24:25], s63, v52
	v_mad_u32_u24 v52, v58, s65, v59
	s_cmp_eq_u32 s28, 0
	v_lshlrev_b32_e32 v140, 3, v58
	v_lshl_add_u64 v[104:105], v[54:55], 0, v[56:57]
	s_mov_b32 s38, 0
	v_cmp_eq_u32_e64 s[16:17], 0, v138
	v_cmp_gt_u32_e64 s[18:19], s63, v60
	v_or_b32_e32 v142, v52, v56
	v_mul_u32_u24_e32 v143, 0x1b0, v138
	s_cselect_b64 s[28:29], -1, 0
	s_and_b64 s[30:31], s[30:31], s[40:41]
	s_and_b64 s[34:35], s[34:35], s[40:41]
	s_and_b64 s[36:37], s[36:37], s[40:41]
	s_mov_b64 s[50:51], -1
	v_add_u32_e32 v144, v62, v84
	s_branch .LBB0_1751
